# P0 weight transposes rewritten: one tile per wave, scalar lookup, 16-B loads, wave-private LDS transpose, no barriers; ada workgroups take fewer tiles
# speedup vs baseline: 1.0299x; 1.0110x over previous
; __device__ __forceinline__ void transpose_load(const TItem& t, int N, float (&v)[8]) {
; #pragma unroll
;     for (int i = 0; i < 8; ++i) v[i] = t.src[(size_t)(8 * i) * N];
; __device__ __forceinline__ void phase0(const Params& P, unsigned char* smem) {
;     ...
;     auto lookup = [&](int it, TItem& t, int& N) {
;         int r = it < total ? it : total - 1;
;         t.src = nullptr; t.dst = nullptr; t.K = 0; t.mode = 0; t.n0 = 0; N = 0;
; #pragma unroll
;         for (int i = 0; i < 11; ++i) {
;             const int cnt = (tw[i].K >> 6) * (tw[i].N >> 5);
;             if (r >= 0 && r < cnt) {
;                 const int nblk = tw[i].N >> 5, kb = r / nblk, nb = r - kb * nblk, k0 = kb * 64, n0 = nb * 32, tid = threadIdx.x & 255;
;                 N = tw[i].N; t.K = tw[i].K; t.mode = tw[i].mode; t.n0 = n0;
;                 t.src = P.in[tw[i].in] + (size_t)(k0 + (tid >> 5)) * tw[i].N + n0 + (tid & 31);
;                 t.dst = (bf16_t*)(P.ws + tw[i].off) + k0 + (tid & 7) * 8;
;             }
;             r -= cnt;
;         }
;     };
;     {
;         const int stride = gridDim.x * 2;
;         int it = blockIdx.x * 2 + hb;
;         TItem cur, nxt; int Nc = 0, Nn = 0; float vn[8];
;         if (blockIdx.x * 2 < total) { lookup(it, nxt, Nn); transpose_load(nxt, Nn, vn); }
;         for (int base = blockIdx.x * 2; base < total; base += stride) {
;             float v[8];
; #pragma unroll
;             for (int i = 0; i < 8; ++i) v[i] = vn[i];
;             cur = nxt; Nc = Nn;
;             if (base + stride < total) { lookup(it + stride, nxt, Nn); transpose_load(nxt, Nn, vn); }
.LBB0_20:
	v_and_b32_e32 v1, 63, v168
	v_lshrrev_b32_e32 v14, 6, v168
	s_nop 1
	v_readfirstlane_b32 s0, v14
	s_nop 3
	v_lshrrev_b32_e32 v2, 3, v1
	v_and_b32_e32 v3, 7, v1
	v_lshrrev_b32_e32 v4, 2, v2
	v_and_b32_e32 v14, 3, v2
	v_lshl_or_b32 v4, v4, 3, v14
	s_mulk_i32 s0, 0x2100
	s_add_u32 s3, s0, 16
	v_mul_u32_u24_e32 v5, 0x84, v2
	v_lshl_add_u32 v5, v3, 4, v5
	v_add_u32_e32 v5, s3, v5
	v_add_u32_e32 v6, 0x420, v5
	v_add_u32_e32 v7, 0x420, v6
	v_add_u32_e32 v8, 0x420, v7
	v_add_u32_e32 v9, 0x420, v8
	v_add_u32_e32 v10, 0x420, v9
	v_add_u32_e32 v11, 0x420, v10
	v_add_u32_e32 v12, 0x420, v11
	v_mul_u32_u24_e32 v13, 0x420, v3
	v_lshl_add_u32 v13, v2, 2, v13
	v_add_u32_e32 v13, s3, v13
	v_lshlrev_b32_e32 v3, 4, v3
	v_lshrrev_b32_e32 v14, 6, v168
	s_nop 1
	v_readfirstlane_b32 s0, v14
	s_nop 3
	s_lshl_b32 s4, s33, 3
	s_add_u32 s0, s0, s4
	s_mov_b32 s1, s0
	s_mov_b32 s2, 0
	s_cmpk_lt_u32 s1, 0x580
	s_cbranch_scc1 .Ltr1_m0
	s_cmpk_lt_u32 s1, 0xb00
	s_cbranch_scc1 .Ltr1_m1
	s_cmpk_lt_u32 s1, 0x1080
	s_cbranch_scc1 .Ltr1_m2
	s_cmpk_lt_u32 s1, 0x1600
	s_cbranch_scc1 .Ltr1_m3
	s_cmpk_lt_u32 s1, 0x1b80
	s_cbranch_scc1 .Ltr1_m4
	s_cmpk_lt_u32 s1, 0x2100
	s_cbranch_scc1 .Ltr1_m5
	s_cmpk_lt_u32 s1, 0x2910
	s_cbranch_scc1 .Ltr1_m6
	s_cmpk_lt_u32 s1, 0x2990
	s_cbranch_scc1 .Ltr1_m7
	s_cmpk_lt_u32 s1, 0x2a90
	s_cbranch_scc1 .Ltr1_m8
	s_cmpk_lt_u32 s1, 0x2b90
	s_cbranch_scc1 .Ltr1_m9
	s_sub_u32 s3, s1, 0x2b90
	v_readlane_b32 s6, v251, 43
	v_readlane_b32 s7, v251, 44
	s_mov_b32 s13, 0x2c00000
	s_mov_b32 s14, 0
	s_branch .Ltr1_c1024_1024
.Ltr1_m9:
	s_sub_u32 s3, s1, 0x2a90
	v_readlane_b32 s6, v251, 41
	v_readlane_b32 s7, v251, 42
	s_mov_b32 s13, 0x2b00000
	s_mov_b32 s14, 0
	s_branch .Ltr1_c512_1024
.Ltr1_m8:
	s_sub_u32 s3, s1, 0x2990
	v_readlane_b32 s6, v251, 33
	v_readlane_b32 s7, v251, 34
	s_mov_b32 s13, 0x2a00000
	s_mov_b32 s14, 0
	s_branch .Ltr1_c512_1024
.Ltr1_m7:
	s_sub_u32 s3, s1, 0x2910
	v_readlane_b32 s6, v251, 29
	v_readlane_b32 s7, v251, 30
	s_mov_b32 s13, 0x2980000
	s_mov_b32 s14, 0
	s_branch .Ltr1_c512_512
.Ltr1_m6:
	s_sub_u32 s3, s1, 0x2100
	v_readlane_b32 s6, v251, 11
	v_readlane_b32 s7, v251, 12
	s_mov_b32 s13, 0x2100000
	s_mov_b32 s14, 3
	s_branch .Ltr1_c1024_4128
.Ltr1_m5:
	s_sub_u32 s3, s1, 0x1b80
	v_readlane_b32 s6, v251, 51
	v_readlane_b32 s7, v251, 52
	s_mov_b32 s13, 0x1b80000
	s_mov_b32 s14, 0
	s_branch .Ltr1_c2816_1024
.Ltr1_m4:
	s_sub_u32 s3, s1, 0x1600
	v_readlane_b32 s6, v251, 49
	v_readlane_b32 s7, v251, 50
	s_mov_b32 s13, 0x1080000
	s_mov_b32 s14, 2
	s_branch .Ltr1_c1024_2816
.Ltr1_m3:
	s_sub_u32 s3, s1, 0x1080
	v_readlane_b32 s6, v251, 47
	v_readlane_b32 s7, v251, 48
	s_mov_b32 s13, 0x1080000
	s_mov_b32 s14, 1
	s_branch .Ltr1_c1024_2816
.Ltr1_m2:
	s_sub_u32 s3, s1, 0xb00
	v_readlane_b32 s6, v251, 7
	v_readlane_b32 s7, v251, 8
	s_mov_b32 s13, 0xb00000
	s_mov_b32 s14, 0
	s_branch .Ltr1_c2816_1024
.Ltr1_m1:
	s_sub_u32 s3, s1, 0x580
	v_readlane_b32 s6, v251, 5
	v_readlane_b32 s7, v251, 6
	s_mov_b32 s13, 0x0
	s_mov_b32 s14, 2
	s_branch .Ltr1_c1024_2816
.Ltr1_m0:
	s_mov_b32 s3, s1
	s_mov_b64 s[6:7], s[50:51]
	s_mov_b32 s13, 0x0
	s_mov_b32 s14, 1
	s_branch .Ltr1_c1024_2816
.Ltr1_c1024_1024:
	s_lshr_b32 s10, s3, 5
	s_and_b32 s11, s3, 31
	s_movk_i32 s8, 0x1000
	s_movk_i32 s16, 0x800
	s_branch .Ltr1_common
.Ltr1_c512_1024:
	s_lshr_b32 s10, s3, 5
	s_and_b32 s11, s3, 31
	s_movk_i32 s8, 0x1000
	s_movk_i32 s16, 0x400
	s_branch .Ltr1_common
.Ltr1_c512_512:
	s_lshr_b32 s10, s3, 4
	s_and_b32 s11, s3, 15
	s_movk_i32 s8, 0x800
	s_movk_i32 s16, 0x400
	s_branch .Ltr1_common
.Ltr1_c1024_4128:
	s_mul_i32 s10, s3, 0x7f02
	s_lshr_b32 s10, s10, 22
	s_mul_i32 s4, s10, 0x81
	s_sub_u32 s11, s3, s4
	s_movk_i32 s8, 0x4080
	s_movk_i32 s16, 0x800
	s_branch .Ltr1_common
.Ltr1_c2816_1024:
	s_lshr_b32 s10, s3, 5
	s_and_b32 s11, s3, 31
	s_movk_i32 s8, 0x1000
	s_movk_i32 s16, 0x1600
	s_branch .Ltr1_common
.Ltr1_c1024_2816:
	s_mul_i32 s10, s3, 0xba2f
	s_lshr_b32 s10, s10, 22
	s_mul_i32 s4, s10, 88
	s_sub_u32 s11, s3, s4
	s_movk_i32 s8, 0x2c00
	s_movk_i32 s16, 0x800
	s_branch .Ltr1_common
.Ltr1_common:
	s_lshl_b32 s9, s8, 3
	s_lshl_b32 s15, s8, 6
	s_mul_i32 s4, s10, s15
	s_lshl_b32 s5, s11, 7
	s_add_u32 s4, s4, s5
	s_add_u32 s6, s6, s4
	s_addc_u32 s7, s7, 0
	s_lshl_b32 s12, s11, 5
	s_mov_b64 s[76:77], 0
	s_cmp_eq_u32 s14, 0
	s_cbranch_scc1 .Ltr1_row
	s_cmp_eq_u32 s14, 3
	s_cbranch_scc1 .Ltr1_mode3
	s_lshr_b32 s4, s12, 7
	s_lshl_b32 s4, s4, 8
	s_and_b32 s5, s12, 0x7f
	s_add_u32 s12, s4, s5
	s_cmp_eq_u32 s14, 2
	s_cselect_b32 s4, 0x80, 0
	s_add_u32 s12, s12, s4
	s_branch .Ltr1_row
.Ltr1_mode3:
	s_cmpk_lt_u32 s12, 0x800
	s_cbranch_scc1 .Ltr1_row
	s_cmpk_lg_u32 s12, 0x800
	s_cbranch_scc1 .Ltr1_m3il
	s_movk_i32 s12, 0x1000
	s_branch .Ltr1_row
.Ltr1_m3il:
	s_mov_b64 s[76:77], -1
	s_cmpk_lt_u32 s12, 0xc20
	s_cbranch_scc0 .Ltr1_m3b
	s_sub_u32 s12, s12, 0x820
	s_lshl_b32 s12, s12, 1
	s_add_u32 s12, s12, 0x800
	s_branch .Ltr1_row
.Ltr1_m3b:
	s_sub_u32 s12, s12, 0xc20
	s_lshl_b32 s12, s12, 1
	s_add_u32 s12, s12, 0x804
.Ltr1_row:
	s_mul_i32 s4, s12, s16
	s_lshl_b32 s5, s10, 7
	s_add_u32 s4, s4, s5
	s_add_u32 s4, s4, s13
	s_add_u32 s72, s68, s4
	s_addc_u32 s73, s69, 0
	s_mov_b32 s74, s16
	s_lshl_b32 s75, s16, 3
	s_cmp_lg_u64 s[76:77], 0
	s_cselect_b32 s4, s16, 0
	s_lshl_b32 s4, s4, 3
	s_add_u32 s75, s75, s4
	v_mad_u32_u24 v96, v2, s8, v3
	v_add_u32_e32 v97, s9, v96
	v_add_u32_e32 v98, s9, v97
	v_add_u32_e32 v99, s9, v98
	v_add_u32_e32 v100, s9, v99
	v_add_u32_e32 v101, s9, v100
	v_add_u32_e32 v102, s9, v101
	v_add_u32_e32 v103, s9, v102
	global_load_dwordx4 v[16:19], v96, s[6:7]
	global_load_dwordx4 v[20:23], v97, s[6:7]
	global_load_dwordx4 v[24:27], v98, s[6:7]
	global_load_dwordx4 v[28:31], v99, s[6:7]
	global_load_dwordx4 v[32:35], v100, s[6:7]
	global_load_dwordx4 v[36:39], v101, s[6:7]
	global_load_dwordx4 v[40:43], v102, s[6:7]
	global_load_dwordx4 v[44:47], v103, s[6:7]
	s_add_u32 s2, s2, 1
	s_cmp_lt_u32 s2, 3
	s_cbranch_scc1 .Ltr2_common
	s_cmpk_lt_u32 s0, 0x240
	s_cbranch_scc1 .Ltr_last0f
	s_cmp_eq_u32 s2, 3
	s_cbranch_scc0 .Ltr2_stride
	s_add_u32 s1, s0, 0x15c0
	s_branch .Ltr2_chk
.Ltr2_stride:
	s_add_u32 s1, s1, 0x5c0
	s_branch .Ltr2_chk
.Ltr2_common:
	s_add_u32 s1, s1, 0x800
.Ltr2_chk:
	s_cmpk_lt_u32 s1, 0x2d90
	s_cbranch_scc0 .Ltr_last0f
	s_cmpk_lt_u32 s1, 0x580
	s_cbranch_scc1 .Ltr3_m0
	s_cmpk_lt_u32 s1, 0xb00
	s_cbranch_scc1 .Ltr3_m1
	s_cmpk_lt_u32 s1, 0x1080
	s_cbranch_scc1 .Ltr3_m2
	s_cmpk_lt_u32 s1, 0x1600
	s_cbranch_scc1 .Ltr3_m3
	s_cmpk_lt_u32 s1, 0x1b80
	s_cbranch_scc1 .Ltr3_m4
	s_cmpk_lt_u32 s1, 0x2100
	s_cbranch_scc1 .Ltr3_m5
	s_cmpk_lt_u32 s1, 0x2910
	s_cbranch_scc1 .Ltr3_m6
	s_cmpk_lt_u32 s1, 0x2990
	s_cbranch_scc1 .Ltr3_m7
	s_cmpk_lt_u32 s1, 0x2a90
	s_cbranch_scc1 .Ltr3_m8
	s_cmpk_lt_u32 s1, 0x2b90
	s_cbranch_scc1 .Ltr3_m9
	s_sub_u32 s3, s1, 0x2b90
	v_readlane_b32 s6, v251, 43
	v_readlane_b32 s7, v251, 44
	s_mov_b32 s13, 0x2c00000
	s_mov_b32 s14, 0
	s_branch .Ltr3_c1024_1024

; __device__ __forceinline__ int map_row(int mode, int n) {
;     if (mode == 1) return ((n >> 7) << 8) + (n & 127);
;     if (mode == 2) return ((n >> 7) << 8) + 128 + (n & 127);
;     if (mode == 3) {
;         if (n < 2048) return n;
;         if (n < 2080) return 4096 + (n - 2048);
;         if (n < 3104) { const int j = n - 2080; return 2048 + ((j >> 4) << 5) + (((j >> 2) & 3) << 3) + (j & 3); }
;         { const int j = n - 3104; return 2048 + ((j >> 4) << 5) + (((j >> 2) & 3) << 3) + 4 + (j & 3); }
;     }
; __device__ __forceinline__ void phase0(const Params& P, unsigned char* smem) {
;     ...
;                 const int nblk = tw[i].N >> 5, kb = r / nblk, nb = r - kb * nblk, k0 = kb * 64, n0 = nb * 32, tid = threadIdx.x & 255;
;                 N = tw[i].N; t.K = tw[i].K; t.mode = tw[i].mode; t.n0 = n0;
;                 t.src = P.in[tw[i].in] + (size_t)(k0 + (tid >> 5)) * tw[i].N + n0 + (tid & 31);
;                 t.dst = (bf16_t*)(P.ws + tw[i].off) + k0 + (tid & 7) * 8;
.Ltr3_common:
	s_lshl_b32 s9, s8, 3
	s_lshl_b32 s15, s8, 6
	s_mul_i32 s4, s10, s15
	s_lshl_b32 s5, s11, 7
	s_add_u32 s4, s4, s5
	s_add_u32 s6, s6, s4
	s_addc_u32 s7, s7, 0
	s_lshl_b32 s12, s11, 5
	s_mov_b64 s[82:83], 0
	s_cmp_eq_u32 s14, 0
	s_cbranch_scc1 .Ltr3_row
	s_cmp_eq_u32 s14, 3
	s_cbranch_scc1 .Ltr3_mode3
	s_lshr_b32 s4, s12, 7
	s_lshl_b32 s4, s4, 8
	s_and_b32 s5, s12, 0x7f
	s_add_u32 s12, s4, s5
	s_cmp_eq_u32 s14, 2
	s_cselect_b32 s4, 0x80, 0
	s_add_u32 s12, s12, s4
	s_branch .Ltr3_row

; __device__ __forceinline__ int map_row(int mode, int n) {
;     ...
;     if (mode == 3) {
;         if (n < 2048) return n;
;         if (n < 2080) return 4096 + (n - 2048);
;         if (n < 3104) { const int j = n - 2080; return 2048 + ((j >> 4) << 5) + (((j >> 2) & 3) << 3) + (j & 3); }
;         { const int j = n - 3104; return 2048 + ((j >> 4) << 5) + (((j >> 2) & 3) << 3) + 4 + (j & 3); }
;     }
.Ltr3_m3il:
	s_mov_b64 s[82:83], -1
	s_cmpk_lt_u32 s12, 0xc20
	s_cbranch_scc0 .Ltr3_m3b
	s_sub_u32 s12, s12, 0x820
	s_lshl_b32 s12, s12, 1
	s_add_u32 s12, s12, 0x800
	s_branch .Ltr3_row

; __device__ __forceinline__ unsigned pk2(float a, float b) { const f32x2_t v = {a, b}; const bf16x2_t r = __builtin_convertvector(v, bf16x2_t); return __builtin_bit_cast(unsigned, r); }
; __device__ __forceinline__ void transpose_load(const TItem& t, int N, float (&v)[8]) {
; #pragma unroll
;     for (int i = 0; i < 8; ++i) v[i] = t.src[(size_t)(8 * i) * N];
; __device__ __forceinline__ void transpose_store(const TItem& t, const float (&v)[8], float* scr) {
;     const int tid = threadIdx.x & 255;
; #pragma unroll
;     for (int i = 0; i < 8; ++i) scr[((tid >> 5) + 8 * i) * 33 + (tid & 31)] = v[i];
;     __syncthreads();
;     const int n = tid >> 3, kc = (tid & 7) * 8;
;     const float* s = scr + kc * 33 + n;
;     uint4 o; o.x = pk2(s[0], s[33]); o.y = pk2(s[66], s[99]); o.z = pk2(s[132], s[165]); o.w = pk2(s[198], s[231]);
;     const int nd = map_row(t.mode, t.n0 + n);
;     *(uint4*)(t.dst + (size_t)nd * t.K) = o;
.Ltr3_row:
	s_mul_i32 s4, s12, s16
	s_lshl_b32 s5, s10, 7
	s_add_u32 s4, s4, s5
	s_add_u32 s4, s4, s13
	s_add_u32 s78, s68, s4
	s_addc_u32 s79, s69, 0
	s_mov_b32 s80, s16
	s_lshl_b32 s81, s16, 3
	s_cmp_lg_u64 s[82:83], 0
	s_cselect_b32 s4, s16, 0
	s_lshl_b32 s4, s4, 3
	s_add_u32 s81, s81, s4
	v_mad_u32_u24 v96, v2, s8, v3
	v_add_u32_e32 v97, s9, v96
	v_add_u32_e32 v98, s9, v97
	v_add_u32_e32 v99, s9, v98
	v_add_u32_e32 v100, s9, v99
	v_add_u32_e32 v101, s9, v100
	v_add_u32_e32 v102, s9, v101
	v_add_u32_e32 v103, s9, v102
	global_load_dwordx4 v[48:51], v96, s[6:7]
	global_load_dwordx4 v[52:55], v97, s[6:7]
	global_load_dwordx4 v[56:59], v98, s[6:7]
	global_load_dwordx4 v[60:63], v99, s[6:7]
	global_load_dwordx4 v[64:67], v100, s[6:7]
	global_load_dwordx4 v[68:71], v101, s[6:7]
	global_load_dwordx4 v[72:75], v102, s[6:7]
	global_load_dwordx4 v[76:79], v103, s[6:7]
	s_waitcnt vmcnt(8)
	ds_write2_b32 v5, v16, v17 offset1:1
	ds_write2_b32 v5, v18, v19 offset0:2 offset1:3
	ds_write2_b32 v6, v20, v21 offset1:1
	ds_write2_b32 v6, v22, v23 offset0:2 offset1:3
	ds_write2_b32 v7, v24, v25 offset1:1
	ds_write2_b32 v7, v26, v27 offset0:2 offset1:3
	ds_write2_b32 v8, v28, v29 offset1:1
	ds_write2_b32 v8, v30, v31 offset0:2 offset1:3
	ds_write2_b32 v9, v32, v33 offset1:1
	ds_write2_b32 v9, v34, v35 offset0:2 offset1:3
	ds_write2_b32 v10, v36, v37 offset1:1
	ds_write2_b32 v10, v38, v39 offset0:2 offset1:3
	ds_write2_b32 v11, v40, v41 offset1:1
	ds_write2_b32 v11, v42, v43 offset0:2 offset1:3
	ds_write2_b32 v12, v44, v45 offset1:1
	ds_write2_b32 v12, v46, v47 offset0:2 offset1:3
	v_cndmask_b32_e64 v14, v2, v4, s[76:77]
	v_mad_u32_u24 v104, v14, s74, v3
	s_add_u32 s20, s72, s75
	s_addc_u32 s21, s73, 0
	s_add_u32 s22, s20, s75
	s_addc_u32 s23, s21, 0
	s_add_u32 s24, s22, s75
	s_addc_u32 s25, s23, 0
	s_waitcnt lgkmcnt(0)
	ds_read2_b32 v[16:17], v13 offset0:0 offset1:33
	ds_read2_b32 v[18:19], v13 offset0:66 offset1:99
	ds_read2_b32 v[20:21], v13 offset0:132 offset1:165
	ds_read2_b32 v[22:23], v13 offset0:198 offset1:231
	ds_read2_b32 v[24:25], v13 offset0:8 offset1:41
	ds_read2_b32 v[26:27], v13 offset0:74 offset1:107
	ds_read2_b32 v[28:29], v13 offset0:140 offset1:173
	ds_read2_b32 v[30:31], v13 offset0:206 offset1:239
	ds_read2_b32 v[32:33], v13 offset0:16 offset1:49
	ds_read2_b32 v[34:35], v13 offset0:82 offset1:115
	ds_read2_b32 v[36:37], v13 offset0:148 offset1:181
	ds_read2_b32 v[38:39], v13 offset0:214 offset1:247
	ds_read2_b32 v[40:41], v13 offset0:24 offset1:57
	ds_read2_b32 v[42:43], v13 offset0:90 offset1:123
	ds_read2_b32 v[44:45], v13 offset0:156 offset1:189
	ds_read2_b32 v[46:47], v13 offset0:222 offset1:255
	s_waitcnt lgkmcnt(12)
	v_cvt_pk_bf16_f32 v80, v16, v17
	v_cvt_pk_bf16_f32 v81, v18, v19
	v_cvt_pk_bf16_f32 v82, v20, v21
	v_cvt_pk_bf16_f32 v83, v22, v23
	global_store_dwordx4 v104, v[80:83], s[72:73]
	s_waitcnt lgkmcnt(8)
	v_cvt_pk_bf16_f32 v84, v24, v25
	v_cvt_pk_bf16_f32 v85, v26, v27
	v_cvt_pk_bf16_f32 v86, v28, v29
	v_cvt_pk_bf16_f32 v87, v30, v31
	global_store_dwordx4 v104, v[84:87], s[20:21]
	s_waitcnt lgkmcnt(4)
	v_cvt_pk_bf16_f32 v88, v32, v33
	v_cvt_pk_bf16_f32 v89, v34, v35
	v_cvt_pk_bf16_f32 v90, v36, v37
	v_cvt_pk_bf16_f32 v91, v38, v39
	global_store_dwordx4 v104, v[88:91], s[22:23]
	s_waitcnt lgkmcnt(0)
	v_cvt_pk_bf16_f32 v92, v40, v41
	v_cvt_pk_bf16_f32 v93, v42, v43
	v_cvt_pk_bf16_f32 v94, v44, v45
	v_cvt_pk_bf16_f32 v95, v46, v47
	global_store_dwordx4 v104, v[92:95], s[24:25]
.Ltr_loop:
	s_add_u32 s2, s2, 1
	s_cmp_lt_u32 s2, 3
	s_cbranch_scc1 .Ltr4_common
	s_cmpk_lt_u32 s0, 0x240
	s_cbranch_scc1 .Ltr_last1
	s_cmp_eq_u32 s2, 3
	s_cbranch_scc0 .Ltr4_stride
	s_add_u32 s1, s0, 0x15c0
	s_branch .Ltr4_chk

; __device__ __forceinline__ unsigned pk2(float a, float b) { const f32x2_t v = {a, b}; const bf16x2_t r = __builtin_convertvector(v, bf16x2_t); return __builtin_bit_cast(unsigned, r); }
; __device__ __forceinline__ void transpose_load(const TItem& t, int N, float (&v)[8]) {
; #pragma unroll
;     for (int i = 0; i < 8; ++i) v[i] = t.src[(size_t)(8 * i) * N];
; __device__ __forceinline__ void transpose_store(const TItem& t, const float (&v)[8], float* scr) {
;     const int tid = threadIdx.x & 255;
; #pragma unroll
;     for (int i = 0; i < 8; ++i) scr[((tid >> 5) + 8 * i) * 33 + (tid & 31)] = v[i];
;     __syncthreads();
;     const int n = tid >> 3, kc = (tid & 7) * 8;
;     const float* s = scr + kc * 33 + n;
;     uint4 o; o.x = pk2(s[0], s[33]); o.y = pk2(s[66], s[99]); o.z = pk2(s[132], s[165]); o.w = pk2(s[198], s[231]);
;     const int nd = map_row(t.mode, t.n0 + n);
;     *(uint4*)(t.dst + (size_t)nd * t.K) = o;
.Ltr5_row:
	s_mul_i32 s4, s12, s16
	s_lshl_b32 s5, s10, 7
	s_add_u32 s4, s4, s5
	s_add_u32 s4, s4, s13
	s_add_u32 s72, s68, s4
	s_addc_u32 s73, s69, 0
	s_mov_b32 s74, s16
	s_lshl_b32 s75, s16, 3
	s_cmp_lg_u64 s[76:77], 0
	s_cselect_b32 s4, s16, 0
	s_lshl_b32 s4, s4, 3
	s_add_u32 s75, s75, s4
	v_mad_u32_u24 v96, v2, s8, v3
	v_add_u32_e32 v97, s9, v96
	v_add_u32_e32 v98, s9, v97
	v_add_u32_e32 v99, s9, v98
	v_add_u32_e32 v100, s9, v99
	v_add_u32_e32 v101, s9, v100
	v_add_u32_e32 v102, s9, v101
	v_add_u32_e32 v103, s9, v102
	global_load_dwordx4 v[16:19], v96, s[6:7]
	global_load_dwordx4 v[20:23], v97, s[6:7]
	global_load_dwordx4 v[24:27], v98, s[6:7]
	global_load_dwordx4 v[28:31], v99, s[6:7]
	global_load_dwordx4 v[32:35], v100, s[6:7]
	global_load_dwordx4 v[36:39], v101, s[6:7]
	global_load_dwordx4 v[40:43], v102, s[6:7]
	global_load_dwordx4 v[44:47], v103, s[6:7]
	s_waitcnt vmcnt(12)
	ds_write2_b32 v5, v48, v49 offset1:1
	ds_write2_b32 v5, v50, v51 offset0:2 offset1:3
	ds_write2_b32 v6, v52, v53 offset1:1
	ds_write2_b32 v6, v54, v55 offset0:2 offset1:3
	ds_write2_b32 v7, v56, v57 offset1:1
	ds_write2_b32 v7, v58, v59 offset0:2 offset1:3
	ds_write2_b32 v8, v60, v61 offset1:1
	ds_write2_b32 v8, v62, v63 offset0:2 offset1:3
	ds_write2_b32 v9, v64, v65 offset1:1
	ds_write2_b32 v9, v66, v67 offset0:2 offset1:3
	ds_write2_b32 v10, v68, v69 offset1:1
	ds_write2_b32 v10, v70, v71 offset0:2 offset1:3
	ds_write2_b32 v11, v72, v73 offset1:1
	ds_write2_b32 v11, v74, v75 offset0:2 offset1:3
	ds_write2_b32 v12, v76, v77 offset1:1
	ds_write2_b32 v12, v78, v79 offset0:2 offset1:3
	v_cndmask_b32_e64 v14, v2, v4, s[82:83]
	v_mad_u32_u24 v104, v14, s80, v3
	s_add_u32 s20, s78, s81
	s_addc_u32 s21, s79, 0
	s_add_u32 s22, s20, s81
	s_addc_u32 s23, s21, 0
	s_add_u32 s24, s22, s81
	s_addc_u32 s25, s23, 0
	s_waitcnt lgkmcnt(0)
	ds_read2_b32 v[48:49], v13 offset0:0 offset1:33
	ds_read2_b32 v[50:51], v13 offset0:66 offset1:99
	ds_read2_b32 v[52:53], v13 offset0:132 offset1:165
	ds_read2_b32 v[54:55], v13 offset0:198 offset1:231
	ds_read2_b32 v[56:57], v13 offset0:8 offset1:41
	ds_read2_b32 v[58:59], v13 offset0:74 offset1:107
	ds_read2_b32 v[60:61], v13 offset0:140 offset1:173
	ds_read2_b32 v[62:63], v13 offset0:206 offset1:239
	ds_read2_b32 v[64:65], v13 offset0:16 offset1:49
	ds_read2_b32 v[66:67], v13 offset0:82 offset1:115
	ds_read2_b32 v[68:69], v13 offset0:148 offset1:181
	ds_read2_b32 v[70:71], v13 offset0:214 offset1:247
	ds_read2_b32 v[72:73], v13 offset0:24 offset1:57
	ds_read2_b32 v[74:75], v13 offset0:90 offset1:123
	ds_read2_b32 v[76:77], v13 offset0:156 offset1:189
	ds_read2_b32 v[78:79], v13 offset0:222 offset1:255
	s_waitcnt lgkmcnt(12)
	v_cvt_pk_bf16_f32 v80, v48, v49
	v_cvt_pk_bf16_f32 v81, v50, v51
	v_cvt_pk_bf16_f32 v82, v52, v53
	v_cvt_pk_bf16_f32 v83, v54, v55
	global_store_dwordx4 v104, v[80:83], s[78:79]
	s_waitcnt lgkmcnt(8)
	v_cvt_pk_bf16_f32 v84, v56, v57
	v_cvt_pk_bf16_f32 v85, v58, v59
	v_cvt_pk_bf16_f32 v86, v60, v61
	v_cvt_pk_bf16_f32 v87, v62, v63
	global_store_dwordx4 v104, v[84:87], s[20:21]
	s_waitcnt lgkmcnt(4)
	v_cvt_pk_bf16_f32 v88, v64, v65
	v_cvt_pk_bf16_f32 v89, v66, v67
	v_cvt_pk_bf16_f32 v90, v68, v69
	v_cvt_pk_bf16_f32 v91, v70, v71
	global_store_dwordx4 v104, v[88:91], s[22:23]
	s_waitcnt lgkmcnt(0)
	v_cvt_pk_bf16_f32 v92, v72, v73
	v_cvt_pk_bf16_f32 v93, v74, v75
	v_cvt_pk_bf16_f32 v94, v76, v77
	v_cvt_pk_bf16_f32 v95, v78, v79
	global_store_dwordx4 v104, v[92:95], s[24:25]
	s_add_u32 s2, s2, 1
	s_cmp_lt_u32 s2, 3
	s_cbranch_scc1 .Ltr6_common
	s_cmpk_lt_u32 s0, 0x240
	s_cbranch_scc1 .Ltr_last0
	s_cmp_eq_u32 s2, 3
	s_cbranch_scc0 .Ltr6_stride
	s_add_u32 s1, s0, 0x15c0
	s_branch .Ltr6_chk

; __device__ __forceinline__ unsigned pk2(float a, float b) { const f32x2_t v = {a, b}; const bf16x2_t r = __builtin_convertvector(v, bf16x2_t); return __builtin_bit_cast(unsigned, r); }
; __device__ __forceinline__ void transpose_load(const TItem& t, int N, float (&v)[8]) {
; #pragma unroll
;     for (int i = 0; i < 8; ++i) v[i] = t.src[(size_t)(8 * i) * N];
; __device__ __forceinline__ void transpose_store(const TItem& t, const float (&v)[8], float* scr) {
;     const int tid = threadIdx.x & 255;
; #pragma unroll
;     for (int i = 0; i < 8; ++i) scr[((tid >> 5) + 8 * i) * 33 + (tid & 31)] = v[i];
;     __syncthreads();
;     const int n = tid >> 3, kc = (tid & 7) * 8;
;     const float* s = scr + kc * 33 + n;
;     uint4 o; o.x = pk2(s[0], s[33]); o.y = pk2(s[66], s[99]); o.z = pk2(s[132], s[165]); o.w = pk2(s[198], s[231]);
;     const int nd = map_row(t.mode, t.n0 + n);
;     *(uint4*)(t.dst + (size_t)nd * t.K) = o;
.Ltr7_row:
	s_mul_i32 s4, s12, s16
	s_lshl_b32 s5, s10, 7
	s_add_u32 s4, s4, s5
	s_add_u32 s4, s4, s13
	s_add_u32 s78, s68, s4
	s_addc_u32 s79, s69, 0
	s_mov_b32 s80, s16
	s_lshl_b32 s81, s16, 3
	s_cmp_lg_u64 s[82:83], 0
	s_cselect_b32 s4, s16, 0
	s_lshl_b32 s4, s4, 3
	s_add_u32 s81, s81, s4
	v_mad_u32_u24 v96, v2, s8, v3
	v_add_u32_e32 v97, s9, v96
	v_add_u32_e32 v98, s9, v97
	v_add_u32_e32 v99, s9, v98
	v_add_u32_e32 v100, s9, v99
	v_add_u32_e32 v101, s9, v100
	v_add_u32_e32 v102, s9, v101
	v_add_u32_e32 v103, s9, v102
	global_load_dwordx4 v[48:51], v96, s[6:7]
	global_load_dwordx4 v[52:55], v97, s[6:7]
	global_load_dwordx4 v[56:59], v98, s[6:7]
	global_load_dwordx4 v[60:63], v99, s[6:7]
	global_load_dwordx4 v[64:67], v100, s[6:7]
	global_load_dwordx4 v[68:71], v101, s[6:7]
	global_load_dwordx4 v[72:75], v102, s[6:7]
	global_load_dwordx4 v[76:79], v103, s[6:7]
	s_waitcnt vmcnt(12)
	ds_write2_b32 v5, v16, v17 offset1:1
	ds_write2_b32 v5, v18, v19 offset0:2 offset1:3
	ds_write2_b32 v6, v20, v21 offset1:1
	ds_write2_b32 v6, v22, v23 offset0:2 offset1:3
	ds_write2_b32 v7, v24, v25 offset1:1
	ds_write2_b32 v7, v26, v27 offset0:2 offset1:3
	ds_write2_b32 v8, v28, v29 offset1:1
	ds_write2_b32 v8, v30, v31 offset0:2 offset1:3
	ds_write2_b32 v9, v32, v33 offset1:1
	ds_write2_b32 v9, v34, v35 offset0:2 offset1:3
	ds_write2_b32 v10, v36, v37 offset1:1
	ds_write2_b32 v10, v38, v39 offset0:2 offset1:3
	ds_write2_b32 v11, v40, v41 offset1:1
	ds_write2_b32 v11, v42, v43 offset0:2 offset1:3
	ds_write2_b32 v12, v44, v45 offset1:1
	ds_write2_b32 v12, v46, v47 offset0:2 offset1:3
	v_cndmask_b32_e64 v14, v2, v4, s[76:77]
	v_mad_u32_u24 v104, v14, s74, v3
	s_add_u32 s20, s72, s75
	s_addc_u32 s21, s73, 0
	s_add_u32 s22, s20, s75
	s_addc_u32 s23, s21, 0
	s_add_u32 s24, s22, s75
	s_addc_u32 s25, s23, 0
	s_waitcnt lgkmcnt(0)
	ds_read2_b32 v[16:17], v13 offset0:0 offset1:33
	ds_read2_b32 v[18:19], v13 offset0:66 offset1:99
	ds_read2_b32 v[20:21], v13 offset0:132 offset1:165
	ds_read2_b32 v[22:23], v13 offset0:198 offset1:231
	ds_read2_b32 v[24:25], v13 offset0:8 offset1:41
	ds_read2_b32 v[26:27], v13 offset0:74 offset1:107
	ds_read2_b32 v[28:29], v13 offset0:140 offset1:173
	ds_read2_b32 v[30:31], v13 offset0:206 offset1:239
	ds_read2_b32 v[32:33], v13 offset0:16 offset1:49
	ds_read2_b32 v[34:35], v13 offset0:82 offset1:115
	ds_read2_b32 v[36:37], v13 offset0:148 offset1:181
	ds_read2_b32 v[38:39], v13 offset0:214 offset1:247
	ds_read2_b32 v[40:41], v13 offset0:24 offset1:57
	ds_read2_b32 v[42:43], v13 offset0:90 offset1:123
	ds_read2_b32 v[44:45], v13 offset0:156 offset1:189
	ds_read2_b32 v[46:47], v13 offset0:222 offset1:255
	s_waitcnt lgkmcnt(12)
	v_cvt_pk_bf16_f32 v80, v16, v17
	v_cvt_pk_bf16_f32 v81, v18, v19
	v_cvt_pk_bf16_f32 v82, v20, v21
	v_cvt_pk_bf16_f32 v83, v22, v23
	global_store_dwordx4 v104, v[80:83], s[72:73]
	s_waitcnt lgkmcnt(8)
	v_cvt_pk_bf16_f32 v84, v24, v25
	v_cvt_pk_bf16_f32 v85, v26, v27
	v_cvt_pk_bf16_f32 v86, v28, v29
	v_cvt_pk_bf16_f32 v87, v30, v31
	global_store_dwordx4 v104, v[84:87], s[20:21]
	s_waitcnt lgkmcnt(4)
	v_cvt_pk_bf16_f32 v88, v32, v33
	v_cvt_pk_bf16_f32 v89, v34, v35
	v_cvt_pk_bf16_f32 v90, v36, v37
	v_cvt_pk_bf16_f32 v91, v38, v39
	global_store_dwordx4 v104, v[88:91], s[22:23]
	s_waitcnt lgkmcnt(0)
	v_cvt_pk_bf16_f32 v92, v40, v41
	v_cvt_pk_bf16_f32 v93, v42, v43
	v_cvt_pk_bf16_f32 v94, v44, v45
	v_cvt_pk_bf16_f32 v95, v46, v47
	global_store_dwordx4 v104, v[92:95], s[24:25]
	s_branch .Ltr_loop
.Ltr_last1:
	s_waitcnt vmcnt(4)
	ds_write2_b32 v5, v48, v49 offset1:1
	ds_write2_b32 v5, v50, v51 offset0:2 offset1:3
	ds_write2_b32 v6, v52, v53 offset1:1
	ds_write2_b32 v6, v54, v55 offset0:2 offset1:3
	ds_write2_b32 v7, v56, v57 offset1:1
	ds_write2_b32 v7, v58, v59 offset0:2 offset1:3
	ds_write2_b32 v8, v60, v61 offset1:1
	ds_write2_b32 v8, v62, v63 offset0:2 offset1:3
	ds_write2_b32 v9, v64, v65 offset1:1
	ds_write2_b32 v9, v66, v67 offset0:2 offset1:3
	ds_write2_b32 v10, v68, v69 offset1:1
	ds_write2_b32 v10, v70, v71 offset0:2 offset1:3
	ds_write2_b32 v11, v72, v73 offset1:1
	ds_write2_b32 v11, v74, v75 offset0:2 offset1:3
	ds_write2_b32 v12, v76, v77 offset1:1
	ds_write2_b32 v12, v78, v79 offset0:2 offset1:3
	v_cndmask_b32_e64 v14, v2, v4, s[82:83]
	v_mad_u32_u24 v104, v14, s80, v3
	s_add_u32 s20, s78, s81
	s_addc_u32 s21, s79, 0
	s_add_u32 s22, s20, s81
	s_addc_u32 s23, s21, 0
	s_add_u32 s24, s22, s81
	s_addc_u32 s25, s23, 0
	s_waitcnt lgkmcnt(0)
	ds_read2_b32 v[48:49], v13 offset0:0 offset1:33
	ds_read2_b32 v[50:51], v13 offset0:66 offset1:99
	ds_read2_b32 v[52:53], v13 offset0:132 offset1:165
	ds_read2_b32 v[54:55], v13 offset0:198 offset1:231
	ds_read2_b32 v[56:57], v13 offset0:8 offset1:41
	ds_read2_b32 v[58:59], v13 offset0:74 offset1:107
	ds_read2_b32 v[60:61], v13 offset0:140 offset1:173
	ds_read2_b32 v[62:63], v13 offset0:206 offset1:239
	ds_read2_b32 v[64:65], v13 offset0:16 offset1:49
	ds_read2_b32 v[66:67], v13 offset0:82 offset1:115
	ds_read2_b32 v[68:69], v13 offset0:148 offset1:181
	ds_read2_b32 v[70:71], v13 offset0:214 offset1:247
	ds_read2_b32 v[72:73], v13 offset0:24 offset1:57
	ds_read2_b32 v[74:75], v13 offset0:90 offset1:123
	ds_read2_b32 v[76:77], v13 offset0:156 offset1:189
	ds_read2_b32 v[78:79], v13 offset0:222 offset1:255
	s_waitcnt lgkmcnt(12)
	v_cvt_pk_bf16_f32 v80, v48, v49
	v_cvt_pk_bf16_f32 v81, v50, v51
	v_cvt_pk_bf16_f32 v82, v52, v53
	v_cvt_pk_bf16_f32 v83, v54, v55
	global_store_dwordx4 v104, v[80:83], s[78:79]
	s_waitcnt lgkmcnt(8)
	v_cvt_pk_bf16_f32 v84, v56, v57
	v_cvt_pk_bf16_f32 v85, v58, v59
	v_cvt_pk_bf16_f32 v86, v60, v61
	v_cvt_pk_bf16_f32 v87, v62, v63
	global_store_dwordx4 v104, v[84:87], s[20:21]
	s_waitcnt lgkmcnt(4)
	v_cvt_pk_bf16_f32 v88, v64, v65
	v_cvt_pk_bf16_f32 v89, v66, v67
	v_cvt_pk_bf16_f32 v90, v68, v69
	v_cvt_pk_bf16_f32 v91, v70, v71
	global_store_dwordx4 v104, v[88:91], s[22:23]
	s_waitcnt lgkmcnt(0)
	v_cvt_pk_bf16_f32 v92, v72, v73
	v_cvt_pk_bf16_f32 v93, v74, v75
	v_cvt_pk_bf16_f32 v94, v76, v77
	v_cvt_pk_bf16_f32 v95, v78, v79
	global_store_dwordx4 v104, v[92:95], s[24:25]
	s_branch .Ltr_done
; __device__ __forceinline__ unsigned pk2(float a, float b) { const f32x2_t v = {a, b}; const bf16x2_t r = __builtin_convertvector(v, bf16x2_t); return __builtin_bit_cast(unsigned, r); }
; __device__ __forceinline__ void transpose_store(const TItem& t, const float (&v)[8], float* scr) {
;     const int tid = threadIdx.x & 255;
; #pragma unroll
;     for (int i = 0; i < 8; ++i) scr[((tid >> 5) + 8 * i) * 33 + (tid & 31)] = v[i];
;     __syncthreads();
;     const int n = tid >> 3, kc = (tid & 7) * 8;
;     const float* s = scr + kc * 33 + n;
;     uint4 o; o.x = pk2(s[0], s[33]); o.y = pk2(s[66], s[99]); o.z = pk2(s[132], s[165]); o.w = pk2(s[198], s[231]);
;     const int nd = map_row(t.mode, t.n0 + n);
;     *(uint4*)(t.dst + (size_t)nd * t.K) = o;
;     __syncthreads();
; }
; __device__ __forceinline__ void phase0(const Params& P, unsigned char* smem) {
;     ...
;     const int gtid = blockIdx.x * NTHR + threadIdx.x, gsz = gridDim.x * NTHR;
;     for (int e = gtid; e < NT + 2 * NL; e += gsz) ((float*)(P.ws + OFF_SS))[e] = 0.f;
.Ltr_last0f:
.Ltr_last0:
	s_waitcnt vmcnt(0)
	ds_write2_b32 v5, v16, v17 offset1:1
	ds_write2_b32 v5, v18, v19 offset0:2 offset1:3
	ds_write2_b32 v6, v20, v21 offset1:1
	ds_write2_b32 v6, v22, v23 offset0:2 offset1:3
	ds_write2_b32 v7, v24, v25 offset1:1
	ds_write2_b32 v7, v26, v27 offset0:2 offset1:3
	ds_write2_b32 v8, v28, v29 offset1:1
	ds_write2_b32 v8, v30, v31 offset0:2 offset1:3
	ds_write2_b32 v9, v32, v33 offset1:1
	ds_write2_b32 v9, v34, v35 offset0:2 offset1:3
	ds_write2_b32 v10, v36, v37 offset1:1
	ds_write2_b32 v10, v38, v39 offset0:2 offset1:3
	ds_write2_b32 v11, v40, v41 offset1:1
	ds_write2_b32 v11, v42, v43 offset0:2 offset1:3
	ds_write2_b32 v12, v44, v45 offset1:1
	ds_write2_b32 v12, v46, v47 offset0:2 offset1:3
	v_cndmask_b32_e64 v14, v2, v4, s[76:77]
	v_mad_u32_u24 v104, v14, s74, v3
	s_add_u32 s20, s72, s75
	s_addc_u32 s21, s73, 0
	s_add_u32 s22, s20, s75
	s_addc_u32 s23, s21, 0
	s_add_u32 s24, s22, s75
	s_addc_u32 s25, s23, 0
	s_waitcnt lgkmcnt(0)
	ds_read2_b32 v[16:17], v13 offset0:0 offset1:33
	ds_read2_b32 v[18:19], v13 offset0:66 offset1:99
	ds_read2_b32 v[20:21], v13 offset0:132 offset1:165
	ds_read2_b32 v[22:23], v13 offset0:198 offset1:231
	ds_read2_b32 v[24:25], v13 offset0:8 offset1:41
	ds_read2_b32 v[26:27], v13 offset0:74 offset1:107
	ds_read2_b32 v[28:29], v13 offset0:140 offset1:173
	ds_read2_b32 v[30:31], v13 offset0:206 offset1:239
	ds_read2_b32 v[32:33], v13 offset0:16 offset1:49
	ds_read2_b32 v[34:35], v13 offset0:82 offset1:115
	ds_read2_b32 v[36:37], v13 offset0:148 offset1:181
	ds_read2_b32 v[38:39], v13 offset0:214 offset1:247
	ds_read2_b32 v[40:41], v13 offset0:24 offset1:57
	ds_read2_b32 v[42:43], v13 offset0:90 offset1:123
	ds_read2_b32 v[44:45], v13 offset0:156 offset1:189
	ds_read2_b32 v[46:47], v13 offset0:222 offset1:255
	s_waitcnt lgkmcnt(12)
	v_cvt_pk_bf16_f32 v80, v16, v17
	v_cvt_pk_bf16_f32 v81, v18, v19
	v_cvt_pk_bf16_f32 v82, v20, v21
	v_cvt_pk_bf16_f32 v83, v22, v23
	global_store_dwordx4 v104, v[80:83], s[72:73]
	s_waitcnt lgkmcnt(8)
	v_cvt_pk_bf16_f32 v84, v24, v25
	v_cvt_pk_bf16_f32 v85, v26, v27
	v_cvt_pk_bf16_f32 v86, v28, v29
	v_cvt_pk_bf16_f32 v87, v30, v31
	global_store_dwordx4 v104, v[84:87], s[20:21]
	s_waitcnt lgkmcnt(4)
	v_cvt_pk_bf16_f32 v88, v32, v33
	v_cvt_pk_bf16_f32 v89, v34, v35
	v_cvt_pk_bf16_f32 v90, v36, v37
	v_cvt_pk_bf16_f32 v91, v38, v39
	global_store_dwordx4 v104, v[88:91], s[22:23]
	s_waitcnt lgkmcnt(0)
	v_cvt_pk_bf16_f32 v92, v40, v41
	v_cvt_pk_bf16_f32 v93, v42, v43
	v_cvt_pk_bf16_f32 v94, v44, v45
	v_cvt_pk_bf16_f32 v95, v46, v47
	global_store_dwordx4 v104, v[92:95], s[24:25]
.Ltr_done:
	v_readlane_b32 s0, v251, 1
	v_readlane_b32 s1, v251, 2
	s_nop 3
	s_load_dword s2, s[0:1], 0x10
	s_waitcnt lgkmcnt(0)
	s_lshr_b32 s0, s2, 16
	s_and_b32 s0, 0xffff, s0
	s_cmp_lg_u32 s0, 0
	s_cselect_b64 s[0:1], -1, 0
	s_cmp_lg_u64 s[0:1], 0
	s_addc_u32 s30, s90, 0
	s_branch .Ltr_pad
	s_nop 0
	s_nop 0
	s_nop 0
	s_nop 0
	s_nop 0
.Ltr_pad:
.LBB0_94:
	v_lshl_add_u32 v2, s33, 9, v168
	s_mov_b32 s0, 0x18400
	s_lshl_b32 s52, s30, 9
	v_cmp_gt_i32_e32 vcc, s0, v2
	s_and_saveexec_b64 s[2:3], vcc
	s_cbranch_execz .LBB0_102
	v_cvt_f32_u32_e32 v1, s52
	v_add_u32_e32 v3, s52, v2
	v_mov_b32_e32 v4, s52
	v_cmp_gt_i32_e32 vcc, s0, v3
	v_rcp_iflag_f32_e32 v1, v1
	s_sub_i32 s4, 0, s52
	v_max_i32_e32 v5, 0x18400, v3
	v_addc_co_u32_e64 v4, s[0:1], v2, v4, vcc
	v_mul_f32_e32 v1, 0x4f7ffffe, v1
	v_cvt_u32_f32_e32 v1, v1
	v_sub_u32_e32 v4, v5, v4
	v_mul_lo_u32 v5, s4, v1
	v_mul_hi_u32 v5, v1, v5
	v_add_u32_e32 v1, v1, v5
	v_mul_hi_u32 v1, v4, v1
	v_mul_lo_u32 v5, v1, s52
	v_sub_u32_e32 v4, v4, v5
	v_add_u32_e32 v6, 1, v1
	v_cmp_le_u32_e64 s[0:1], s52, v4
	v_subrev_u32_e32 v5, s52, v4
	s_mov_b64 s[4:5], -1
	v_cndmask_b32_e64 v1, v1, v6, s[0:1]
	v_cndmask_b32_e64 v4, v4, v5, s[0:1]
	v_add_u32_e32 v5, 1, v1
	v_cmp_le_u32_e64 s[0:1], s52, v4
	v_mov_b32_e32 v4, v2
	s_nop 0
	v_cndmask_b32_e64 v1, v1, v5, s[0:1]
	v_addc_co_u32_e32 v1, vcc, 1, v1, vcc
	v_cmp_lt_u32_e32 vcc, 1, v1
	s_and_saveexec_b64 s[0:1], vcc
	s_cbranch_execz .LBB0_99
	s_add_u32 s4, s68, 0x1ef41000
	s_addc_u32 s5, s69, 0
	v_and_b32_e32 v6, -2, v1
	s_lshl_b32 s7, s30, 10
	s_mov_b32 s20, s7
	s_mov_b64 s[10:11], 0
	v_mov_b32_e32 v7, 0
	v_mov_b32_e32 v8, v6
	v_mov_b64_e32 v[4:5], v[2:3]
